# phase C deal: sample attention passes swapped onto two-pass workgroups with one M1 item (they were the critical path)
# baseline (speedup 1.0000x reference)
.LBB0_259:
	s_or_b64 exec, exec, s[0:1]
	v_readlane_b32 s0, v254, 21
	s_lshl_b32 s21, s0, 9
	s_lshl_b32 s0, s18, 3
	s_add_i32 s19, s24, 0x12000
	s_add_i32 s20, s24, 0x14800
	s_lshl_b32 s22, s18, 5
	s_lshl_b32 s23, s13, 5
	s_add_i32 s26, s0, 0xfffff000
	s_lshl_b32 s27, s13, 3
	s_waitcnt lgkmcnt(0)
	s_barrier
	s_mov_b32 s32, s18
	s_branch .LBB0_262

.LBB0_261:
	s_add_i32 s32, s32, s13
	s_cmp_ge_i32 s32, s15
	s_cbranch_scc1 .LBB0_310
.LBB0_262:
	s_mov_b32 s18, s32
	s_sub_i32 s0, s32, 0x1c2
	s_cmp_lt_i32 s0, 39
	s_cbranch_scc1 .Lrd_done
	s_cmp_gt_i32 s0, 48
	s_cbranch_scc1 .Lrd_hi
	s_cmp_eq_u32 s0, 42
	s_cbranch_scc1 .Lrd_done
	s_cmp_eq_u32 s0, 46
	s_cbranch_scc1 .Lrd_done
	s_sub_i32 s1, s0, 39
	s_cmp_gt_i32 s0, 42
	s_cselect_b32 s2, 1, 0
	s_sub_i32 s1, s1, s2
	s_cmp_gt_i32 s0, 46
	s_cselect_b32 s2, 1, 0
	s_sub_i32 s1, s1, s2
	s_add_i32 s18, s1, 0x200
	s_branch .Lrd_done
.Lrd_hi:
	s_cmp_lt_i32 s0, 62
	s_cbranch_scc1 .Lrd_done
	s_sub_i32 s1, s0, 62
	s_cmp_gt_i32 s1, 2
	s_cselect_b32 s2, 1, 0
	s_add_i32 s3, s1, s2
	s_cmp_gt_i32 s1, 5
	s_cselect_b32 s2, 1, 0
	s_add_i32 s3, s3, s2
	s_add_i32 s18, s3, 0x1e9
.Lrd_done:
	s_lshl_b32 s22, s18, 5
	s_lshl_b32 s26, s18, 3
	s_add_i32 s26, s26, 0xfffff000
	s_cmpk_lt_i32 s18, 0x200
	s_mov_b64 s[0:1], -1
	s_cbranch_scc0 .LBB0_285
	s_mov_b64 s[8:9], s[36:37]
	v_mov_b32_e32 v12, v224
	s_load_dwordx2 s[2:3], s[8:9], 0xa8
	s_and_b32 s6, s22, 0xffffe000
	s_bfe_u32 s7, s18, 0x70001
	v_ashrrev_i32_e32 v0, 6, v12
	s_movk_i32 s4, 0x2400
	s_waitcnt lgkmcnt(0)
	s_add_u32 s0, s2, 0x6000000
	s_addc_u32 s1, s3, 0
	v_mul_lo_u32 v4, v0, s4
	s_lshl_b32 s4, s18, 5
	v_and_b32_e32 v252, 31, v12
	v_mul_lo_u32 v0, v0, s61
	s_and_b32 s11, s4, 0xffffe000
	s_lshl_b32 s5, s7, 6
	s_and_b32 s10, s4, 32
	v_add_u32_e32 v246, s19, v0
	s_or_b32 s5, s5, s11
	v_or_b32_e32 v0, s10, v252
	s_waitcnt vmcnt(10)
	v_or_b32_e32 v162, s5, v0
	v_mov_b64_e32 v[0:1], s[0:1]
	s_movk_i32 s4, 0x1c00
	v_mad_i64_i32 v[0:1], s[4:5], v162, s4, v[0:1]
	s_sub_i32 s4, 8, s7
	s_cmp_lt_u32 s7, 8
	s_cselect_b32 s29, s4, 0
	s_add_i32 s4, s29, s7
	s_lshl_b32 s7, s4, 6
	v_and_b32_e32 v164, 0xffffffc0, v12
	s_add_i32 s4, s11, s7
	v_ashrrev_i32_e32 v165, 31, v164
	s_addk_i32 s4, 0xfe00
	v_bfe_u32 v13, v12, 5, 1
	v_lshlrev_b64 v[2:3], 1, v[164:165]
	s_mul_hi_i32 s5, s4, 0x1c00
	s_mulk_i32 s4, 0x1c00
	v_lshl_add_u64 v[0:1], v[0:1], 0, v[2:3]
	v_lshlrev_b32_e32 v112, 4, v13
	s_add_u32 s4, s0, s4
	v_lshl_add_u64 v[0:1], v[0:1], 0, v[112:113]
	v_add_u32_e32 v15, s24, v4
	s_addc_u32 s5, s1, s5
	v_mul_u32_u24_e32 v4, 0xe00, v252
	global_load_dwordx4 v[64:67], v[0:1], off
	global_load_dwordx4 v[68:71], v[0:1], off offset:32
	global_load_dwordx4 v[72:75], v[0:1], off offset:64
	global_load_dwordx4 v[76:79], v[0:1], off offset:96
	v_lshl_add_u64 v[0:1], s[4:5], 0, v[2:3]
	v_lshlrev_b32_e32 v4, 1, v4
	v_mov_b32_e32 v5, v113
	v_lshl_add_u64 v[6:7], v[0:1], 0, v[4:5]
	v_lshl_add_u64 v[6:7], v[6:7], 0, v[112:113]
	ds_read_b32 v166, v246 offset:1276
	v_bfe_u32 v216, v12, 3, 3
	v_and_b32_e32 v217, 7, v12
	v_lshlrev_b32_e32 v213, 1, v164
	v_mad_u32_u24 v213, v216, v238, v213
	v_lshl_add_u32 v213, v217, 4, v213
	v_add_u32_e32 v213, 0x400, v213
	v_mul_u32_u24_e32 v214, 0x48, v164
	v_add_u32_e32 v214, 0x15000, v214
	v_add_u32_e32 v214, s24, v214
	v_mul_u32_u24_e32 v215, 0x90, v252
	v_lshl_add_u32 v215, v13, 4, v215
	v_add_u32_e32 v215, v215, v214
	v_mul_u32_u24_e32 v218, 0x90, v216
	v_lshl_add_u32 v218, v217, 4, v218
	v_add_u32_e32 v214, v214, v218
	s_mov_b64 s[38:39], s[4:5]
	global_load_dwordx4 v[80:83], v213, s[38:39]
	s_add_u32 s38, s38, 0xe000
	s_addc_u32 s39, s39, 0
	global_load_dwordx4 v[84:87], v213, s[38:39]
	s_add_u32 s38, s38, 0xe000
	s_addc_u32 s39, s39, 0
	global_load_dwordx4 v[88:91], v213, s[38:39]
	s_add_u32 s38, s38, 0xe000
	s_addc_u32 s39, s39, 0
	global_load_dwordx4 v[92:95], v213, s[38:39]
	s_add_u32 s38, s38, 0xe000
	s_addc_u32 s39, s39, 0
	v_bfe_u32 v16, v12, 3, 3
	v_lshlrev_b32_e32 v6, 4, v12
	v_and_b32_e32 v6, 0x70, v6
	v_mov_b32_e32 v7, v113
	v_mul_u32_u24_e32 v34, 0xe00, v16
	v_lshl_add_u64 v[0:1], v[0:1], 0, v[6:7]
	v_lshlrev_b32_e32 v8, 1, v34
	v_mov_b32_e32 v9, v113
	v_lshl_add_u64 v[8:9], v[0:1], 0, v[8:9]
	s_mov_b32 s4, 0xe000
	v_add_co_u32_e32 v10, vcc, s4, v8
	s_mov_b32 s4, 0x1c000
	s_nop 0
	v_addc_co_u32_e32 v11, vcc, 0, v9, vcc
	global_load_dwordx4 v[96:99], v[8:9], off offset:2048
	global_load_dwordx4 v[100:103], v[10:11], off offset:2048
	v_add_co_u32_e32 v10, vcc, s4, v8
	s_mov_b32 s4, 0x2a000
	s_nop 0
	v_addc_co_u32_e32 v11, vcc, 0, v9, vcc
	v_add_co_u32_e32 v8, vcc, s4, v8
	s_movk_i32 s4, 0xe00
	s_nop 0
	v_addc_co_u32_e32 v9, vcc, 0, v9, vcc
	global_load_dwordx4 v[104:107], v[10:11], off offset:2048
	global_load_dwordx4 v[108:111], v[8:9], off offset:2048
	v_mov_b32_e32 v8, 0x1c000
	v_mad_u32_u24 v36, v16, s4, v8
	v_mov_b32_e32 v10, 0x23000
	v_lshlrev_b32_e32 v8, 1, v36
	v_mov_b32_e32 v9, v113
	v_mad_u32_u24 v38, v16, s4, v10
	v_lshl_add_u64 v[8:9], v[0:1], 0, v[8:9]
	v_lshlrev_b32_e32 v10, 1, v38
	v_mov_b32_e32 v11, v113
	v_lshl_add_u64 v[10:11], v[0:1], 0, v[10:11]
	global_load_dwordx4 v[114:117], v[8:9], off offset:2048
	global_load_dwordx4 v[118:121], v[10:11], off offset:2048
	v_mov_b32_e32 v8, 0x2a000
	v_mad_u32_u24 v40, v16, s4, v8
	v_mov_b32_e32 v10, 0x31000
	v_lshlrev_b32_e32 v8, 1, v40
	v_mov_b32_e32 v9, v113
	v_mad_u32_u24 v42, v16, s4, v10
	v_lshl_add_u64 v[8:9], v[0:1], 0, v[8:9]
	v_lshlrev_b32_e32 v10, 1, v42
	v_mov_b32_e32 v11, v113
	v_lshl_add_u64 v[0:1], v[0:1], 0, v[10:11]
	global_load_dwordx4 v[122:125], v[8:9], off offset:2048
	global_load_dwordx4 v[126:129], v[0:1], off offset:2048
	global_load_dwordx4 v[146:149], v213, s[38:39]
	s_add_u32 s38, s38, 0xe000
	s_addc_u32 s39, s39, 0
	global_load_dwordx4 v[150:153], v213, s[38:39]
	s_add_u32 s38, s38, 0xe000
	s_addc_u32 s39, s39, 0
	global_load_dwordx4 v[154:157], v213, s[38:39]
	s_add_u32 s38, s38, 0xe000
	s_addc_u32 s39, s39, 0
	global_load_dwordx4 v[158:161], v213, s[38:39]
	v_lshrrev_b32_e32 v14, 2, v12
	v_lshl_add_u64 v[0:1], s[0:1], 0, v[2:3]
	v_lshlrev_b32_e32 v199, 2, v13
	v_lshlrev_b32_e32 v17, 3, v12
	v_lshl_add_u64 v[168:169], v[0:1], 0, v[4:5]
	v_and_or_b32 v2, v14, 3, v199
	v_lshlrev_b32_e32 v3, 1, v12
	v_lshl_add_u64 v[184:185], v[0:1], 0, v[6:7]
	v_and_or_b32 v0, s22, 32, v252
	v_mul_u32_u24_e32 v2, 0x90, v2
	v_and_b32_e32 v35, 32, v3
	v_and_b32_e32 v3, 24, v17
	s_add_i32 s0, s6, s7
	v_or_b32_e32 v0, 0x200, v0
	v_lshlrev_b32_e32 v32, 3, v13
	v_add_u32_e32 v33, v15, v6
	v_add3_u32 v37, v15, v2, v3
	v_mul_u32_u24_e32 v39, 0x90, v16
	s_add_i32 s11, s0, 0xfffffe00
	v_sub_u32_e32 v0, v0, v199
	s_lshl_b32 s0, s29, 6
	v_mov_b32_e32 v251, 0
	v_mov_b32_e32 v248, v224
	v_and_b32_e32 v232, 63, v12
	v_ashrrev_i32_e32 v163, 31, v162
	s_waitcnt lgkmcnt(0)
	v_mov_b32_e32 v167, v166
	v_mov_b32_e32 v170, v166
	v_mov_b32_e32 v171, v166
	v_mov_b32_e32 v172, v166
	v_mov_b32_e32 v173, v166
	v_mov_b32_e32 v174, v166
	v_mov_b32_e32 v175, v166
	v_mov_b32_e32 v176, v166
	v_mov_b32_e32 v177, v166
	v_mov_b32_e32 v178, v166
	v_mov_b32_e32 v179, v166
	v_mov_b32_e32 v180, v166
	v_mov_b32_e32 v181, v166
	v_mov_b32_e32 v182, v166
	v_mov_b32_e32 v183, v166
	v_lshl_add_u64 v[186:187], v[168:169], 0, v[112:113]
	s_add_i32 s28, s29, -1
	v_subrev_u32_e32 v247, s0, v0
	v_mov_b32_e32 v16, v113
	v_mov_b32_e32 v17, v113
	v_mov_b32_e32 v18, v113
	v_mov_b32_e32 v19, v113
	v_mov_b32_e32 v20, v113
	v_mov_b32_e32 v21, v113
	v_mov_b32_e32 v22, v113
	v_mov_b32_e32 v23, v113
	v_mov_b32_e32 v24, v113
	v_mov_b32_e32 v25, v113
	v_mov_b32_e32 v26, v113
	v_mov_b32_e32 v27, v113
	v_mov_b32_e32 v28, v113
	v_mov_b32_e32 v29, v113
	v_mov_b32_e32 v30, v113
	v_mov_b32_e32 v31, v113
	v_mov_b32_e32 v0, v113
	v_mov_b32_e32 v1, v113
	v_mov_b32_e32 v2, v113
	v_mov_b32_e32 v3, v113
	v_mov_b32_e32 v4, v113
	v_mov_b32_e32 v6, v113
	v_mov_b32_e32 v8, v113
	v_mov_b32_e32 v9, v113
	v_mov_b32_e32 v10, v113
	v_mov_b32_e32 v12, v113
	v_mov_b32_e32 v13, v113
	v_mov_b32_e32 v14, v113
	v_mov_b32_e32 v15, v113
	v_mov_b32_e32 v233, 0xf149f2ca
	v_add_u32_e32 v245, v33, v39
	v_lshlrev_b32_e32 v188, 1, v34
	v_lshlrev_b32_e32 v190, 1, v36
	v_lshlrev_b32_e32 v192, 1, v38
	v_lshlrev_b32_e32 v194, 1, v40
	v_lshlrev_b32_e32 v196, 1, v42
	v_lshlrev_b32_e32 v112, 1, v32
	v_add_u32_e32 v250, v37, v35
	s_waitcnt vmcnt(12)
	ds_write_b128 v214, v[80:83]
	ds_write_b128 v214, v[84:87] offset:1152
	ds_write_b128 v214, v[88:91] offset:2304
	ds_write_b128 v214, v[92:95] offset:3456
